# GEMM K-loops: one static s_setprio 1 for the late-starting wave half (waves 4-7), per-phase flips deleted, reset at phase end
# baseline (speedup 1.0000x reference)
.LBB0_452:
	s_and_b64 vcc, exec, s[8:9]
	s_cbranch_vccz .LBB0_572
	v_readlane_b32 s4, v252, 38
	v_readlane_b32 s5, v252, 39
	s_andn2_b64 vcc, exec, s[4:5]
	v_readfirstlane_b32 s0, v191
	s_cbranch_vccnz .LBB0_758
	v_lshlrev_b32_e32 v0, 4, v191
	v_add_u32_e32 v1, 0x2000, v0
	v_ashrrev_i32_e32 v2, 31, v1
	v_lshrrev_b32_e32 v2, 22, v2
	v_add_u32_e32 v2, v1, v2
	v_ashrrev_i32_e32 v2, 10, v2
	v_mul_i32_i24_e32 v3, 0x400, v2
	v_sub_u32_e32 v1, v1, v3
	v_lshrrev_b32_e32 v3, 4, v1
	v_bitop3_b32 v1, v3, v1, 32 bitop3:0x6c
	v_ashrrev_i32_e32 v3, 31, v1
	v_lshrrev_b32_e32 v3, 26, v3
	v_add_u32_e32 v3, v1, v3
	v_lshlrev_b32_e32 v5, 3, v2
	v_ashrrev_i32_e32 v4, 6, v3
	v_and_b32_e32 v5, -16, v5
	v_add_u32_e32 v5, v4, v5
	v_and_b32_e32 v4, 3, v4
	s_mov_b32 s6, 0x7fffffe0
	v_lshrrev_b32_e32 v6, 2, v5
	v_lshlrev_b32_e32 v7, 1, v5
	v_lshlrev_b32_e32 v2, 5, v2
	v_and_or_b32 v4, v5, s6, v4
	v_and_b32_e32 v6, 4, v6
	v_and_b32_e32 v7, 24, v7
	v_and_b32_e32 v12, 32, v2
	v_and_b32_e32 v2, 0xc0, v3
	v_or3_b32 v4, v4, v6, v7
	v_sub_u32_e32 v1, v1, v2
	v_mov_b32_e32 v7, 1
	v_ashrrev_i16_sdwa v1, v7, sext(v1) dst_sel:DWORD dst_unused:UNUSED_PAD src0_sel:DWORD src1_sel:BYTE_0
	s_waitcnt lgkmcnt(0)
	v_bfe_i32 v13, v1, 0, 16
	v_mul_lo_u32 v4, s61, v4
	v_add_u32_e32 v1, v12, v13
	v_mul_lo_u32 v14, s61, v5
	v_add_lshl_u32 v158, v4, v1, 1
	v_add_lshl_u32 v160, v14, v1, 1
	v_bfe_i32 v1, v191, 27, 1
	v_lshrrev_b32_e32 v1, 22, v1
	v_add_u32_e32 v1, v0, v1
	v_and_b32_e32 v1, 0xfffffc00, v1
	v_sub_u32_e32 v0, v0, v1
	v_lshrrev_b32_e32 v1, 4, v0
	v_ashrrev_i32_e32 v3, 31, v191
	v_bitop3_b32 v0, v1, v0, 32 bitop3:0x6c
	v_lshrrev_b32_e32 v3, 26, v3
	v_ashrrev_i32_e32 v1, 31, v0
	v_add_u32_e32 v3, v191, v3
	v_lshrrev_b32_e32 v1, 26, v1
	v_ashrrev_i32_e32 v3, 6, v3
	v_add_u32_e32 v1, v0, v1
	v_lshlrev_b32_e32 v4, 3, v3
	v_ashrrev_i32_e32 v2, 6, v1
	v_and_b32_e32 v4, -16, v4
	v_add_u32_e32 v4, v2, v4
	v_and_b32_e32 v2, 3, v2
	s_lshl_b32 s54, s61, 9
	v_and_or_b32 v2, v4, s6, v2
	v_readlane_b32 s6, v253, 33
	v_and_b32_e32 v1, 0xc0, v1
	s_mul_hi_i32 s10, s54, s6
	s_mul_i32 s11, s54, s6
	v_readlane_b32 s6, v253, 35
	s_ashr_i32 s5, s0, 6
	v_lshrrev_b32_e32 v5, 2, v4
	v_lshlrev_b32_e32 v6, 1, v4
	v_sub_u32_e32 v0, v0, v1
	v_readlane_b32 s7, v253, 36
	s_mov_b32 s8, s6
	s_ashr_i32 s4, s0, 8
	s_lshl_b32 s14, s61, 8
	s_lshl_b32 s55, s5, 10
	v_and_b32_e32 v5, 4, v5
	v_and_b32_e32 v6, 24, v6
	v_lshlrev_b32_e32 v3, 5, v3
	v_ashrrev_i16_sdwa v0, v7, sext(v0) dst_sel:DWORD dst_unused:UNUSED_PAD src0_sel:DWORD src1_sel:BYTE_0
	s_mul_i32 s7, s54, s8
	v_or3_b32 v2, v2, v5, v6
	v_and_b32_e32 v15, 32, v3
	v_bfe_i32 v16, v0, 0, 16
	s_mul_hi_i32 s6, s54, s6
	s_add_u32 s8, s42, s7
	v_mul_lo_u32 v2, s61, v2
	v_add_u32_e32 v0, v15, v16
	s_addc_u32 s9, s43, s6
	s_add_i32 s64, s55, 0
	v_add_lshl_u32 v162, v2, v0, 1
	s_add_i32 m0, s64, 0x10000
	v_mul_lo_u32 v17, s61, v4
	global_load_lds_dwordx4 v162, s[8:9]
	s_add_i32 m0, s64, 0x12000
	s_add_u32 s6, s8, s14
	global_load_lds_dwordx4 v158, s[8:9]
	s_addc_u32 s7, s9, 0
	s_add_i32 m0, s64, 0x14000
	v_mov_b32_e32 v163, v153
	global_load_lds_dwordx4 v162, s[6:7]
	s_add_i32 m0, s64, 0x16000
	s_add_u32 s52, s46, s11
	v_mov_b32_e32 v159, v153
	s_addc_u32 s53, s47, s10
	s_add_i32 s65, s64, 0x2000
	v_add_lshl_u32 v164, v17, v0, 1
	v_lshl_add_u64 v[4:5], s[6:7], 0, v[162:163]
	v_lshl_add_u64 v[6:7], s[6:7], 0, v[158:159]
	global_load_lds_dwordx4 v158, s[6:7]
	s_mov_b32 m0, s64
	s_add_u32 s6, s52, s14
	global_load_lds_dwordx4 v164, s[52:53]
	s_mov_b32 m0, s65
	s_addc_u32 s7, s53, 0
	s_add_i32 s66, s64, 0x4000
	global_load_lds_dwordx4 v160, s[52:53]
	s_mov_b32 m0, s66
	s_add_i32 s67, s64, 0x6000
	global_load_lds_dwordx4 v164, s[6:7]
	s_mov_b32 m0, s67
	v_mov_b32_e32 v165, v153
	global_load_lds_dwordx4 v160, s[6:7]
	v_mov_b32_e32 v161, v153
	s_cmp_eq_u32 s4, 1
	s_mov_b32 s15, s1
	v_mov_b32_e32 v154, 1
	v_lshl_add_u64 v[0:1], s[8:9], 0, v[162:163]
	v_lshl_add_u64 v[2:3], s[8:9], 0, v[158:159]
	v_lshl_add_u64 v[8:9], s[52:53], 0, v[164:165]
	v_lshl_add_u64 v[10:11], s[52:53], 0, v[160:161]
	s_cselect_b64 s[16:17], -1, 0
	s_cmp_lg_u32 s4, 1
	s_cbranch_scc1 .LBB0_456
	s_barrier
	s_setprio 1

.LBB0_576:
	v_ashrrev_i32_e32 v1, 31, v191
	v_lshrrev_b32_e32 v1, 26, v1
	v_add_u32_e32 v1, v191, v1
	v_ashrrev_i32_e32 v178, 6, v1
	v_bfe_i32 v1, v191, 27, 1
	v_lshlrev_b32_e32 v0, 4, v191
	v_lshrrev_b32_e32 v1, 22, v1
	v_add_u32_e32 v1, v0, v1
	v_and_b32_e32 v1, 0xfffffc00, v1
	v_sub_u32_e32 v1, v0, v1
	v_lshrrev_b32_e32 v2, 4, v1
	v_bitop3_b32 v1, v2, v1, 32 bitop3:0x6c
	v_ashrrev_i32_e32 v3, 31, v1
	v_lshrrev_b32_e32 v3, 26, v3
	v_lshlrev_b32_e32 v2, 3, v178
	v_add_u32_e32 v3, v1, v3
	v_and_b32_e32 v2, -16, v2
	v_ashrrev_i32_e32 v179, 6, v3
	v_add_u32_e32 v181, v179, v2
	v_lshlrev_b32_e32 v2, 5, v178
	v_and_b32_e32 v12, 32, v2
	v_and_b32_e32 v2, 0xc0, v3
	v_sub_u32_e32 v1, v1, v2
	v_mov_b32_e32 v5, 1
	v_ashrrev_i16_sdwa v1, v5, sext(v1) dst_sel:DWORD dst_unused:UNUSED_PAD src0_sel:DWORD src1_sel:BYTE_0
	v_bfe_i32 v180, v1, 0, 16
	v_lshlrev_b32_e32 v1, 1, v181
	v_and_b32_e32 v194, 24, v1
	v_lshrrev_b32_e32 v1, 2, v181
	v_add_u32_e32 v0, 0x2000, v0
	v_and_b32_e32 v195, 4, v1
	v_ashrrev_i32_e32 v1, 31, v0
	v_lshrrev_b32_e32 v1, 22, v1
	v_add_u32_e32 v1, v0, v1
	v_ashrrev_i32_e32 v1, 10, v1
	v_mul_i32_i24_e32 v2, 0x400, v1
	v_sub_u32_e32 v0, v0, v2
	v_lshrrev_b32_e32 v2, 4, v0
	v_bitop3_b32 v0, v2, v0, 32 bitop3:0x6c
	v_ashrrev_i32_e32 v3, 31, v0
	v_lshrrev_b32_e32 v3, 26, v3
	v_lshlrev_b32_e32 v2, 3, v1
	v_add_u32_e32 v3, v0, v3
	v_lshlrev_b32_e32 v1, 5, v1
	s_waitcnt lgkmcnt(0)
	v_and_b32_e32 v13, 32, v1
	v_and_b32_e32 v1, 0xc0, v3
	v_and_b32_e32 v2, -16, v2
	v_ashrrev_i32_e32 v4, 6, v3
	v_sub_u32_e32 v0, v0, v1
	v_add_u32_e32 v197, v4, v2
	v_ashrrev_i16_sdwa v0, v5, sext(v0) dst_sel:DWORD dst_unused:UNUSED_PAD src0_sel:DWORD src1_sel:BYTE_0
	v_bfe_i32 v14, v0, 0, 16
	v_lshlrev_b32_e32 v0, 1, v197
	v_and_b32_e32 v199, 24, v0
	v_lshrrev_b32_e32 v0, 2, v197
	v_and_b32_e32 v200, 4, v0
	v_lshrrev_b32_e32 v0, 1, v191
	v_and_b32_e32 v174, 15, v191
	v_and_b32_e32 v175, 24, v0
	v_lshlrev_b32_e32 v1, 2, v191
	v_lshlrev_b32_e32 v176, 1, v175
	v_lshlrev_b32_e32 v0, 6, v174
	v_and_b32_e32 v1, 32, v1
	v_add_u32_e32 v193, v12, v180
	v_and_b32_e32 v196, 3, v179
	v_mov_b32_e32 v154, 1
	v_add_u32_e32 v198, v13, v14
	v_and_b32_e32 v201, 3, v4
	s_andn2_b64 vcc, exec, s[4:5]
	v_bitop3_b32 v177, v176, v1, v0 bitop3:0x36
	s_cbranch_vccnz .LBB0_700
	s_mov_b32 s0, 0x7fffffe0
	v_and_or_b32 v0, v181, s0, v196
	v_or3_b32 v0, v0, v195, v194
	s_ashr_i32 s4, s6, 6
	v_mul_lo_u32 v0, s61, v0
	s_lshl_b32 s29, s61, 9
	v_add_lshl_u32 v152, v0, v193, 1
	v_and_or_b32 v0, v197, s0, v201
	s_ashr_i32 s5, s6, 8
	s_lshl_b32 s0, s61, 8
	s_lshl_b32 s44, s4, 10
	s_mul_i32 s13, s29, s72
	s_mul_hi_i32 s12, s29, s72
	s_add_u32 s22, s42, s13
	s_addc_u32 s23, s43, s12
	s_add_i32 s45, s44, 0
	v_or3_b32 v0, v0, v200, v199
	s_add_i32 m0, s45, 0x10000
	v_mul_lo_u32 v0, s61, v0
	global_load_lds_dwordx4 v152, s[22:23]
	s_add_i32 m0, s45, 0x12000
	v_add_lshl_u32 v148, v0, v198, 1
	s_add_u32 s12, s22, s0
	global_load_lds_dwordx4 v148, s[22:23]
	s_addc_u32 s13, s23, 0
	s_add_i32 m0, s45, 0x14000
	s_mul_i32 s11, s29, s71
	global_load_lds_dwordx4 v152, s[12:13]
	s_add_i32 m0, s45, 0x16000
	s_mul_hi_i32 s7, s29, s71
	s_add_u32 s24, s46, s11
	v_mul_lo_u32 v15, s61, v181
	s_addc_u32 s25, s47, s7
	s_add_i32 s48, s45, 0x2000
	v_add_lshl_u32 v144, v15, v193, 1
	v_mul_lo_u32 v16, s61, v197
	global_load_lds_dwordx4 v148, s[12:13]
	s_mov_b32 m0, s45
	s_add_u32 s14, s24, s0
	v_add_lshl_u32 v146, v16, v198, 1
	global_load_lds_dwordx4 v144, s[24:25]
	s_mov_b32 m0, s48
	s_addc_u32 s15, s25, 0
	s_add_i32 s49, s45, 0x4000
	global_load_lds_dwordx4 v146, s[24:25]
	s_mov_b32 m0, s49
	s_add_i32 s52, s45, 0x6000
	global_load_lds_dwordx4 v144, s[14:15]
	s_mov_b32 m0, s52
	v_mov_b32_e32 v149, v153
	global_load_lds_dwordx4 v146, s[14:15]
	v_mov_b32_e32 v145, v153
	v_mov_b32_e32 v147, v153
	s_cmp_eq_u32 s5, 1
	v_lshl_add_u64 v[8:9], s[22:23], 0, v[152:153]
	v_lshl_add_u64 v[4:5], s[22:23], 0, v[148:149]
	v_lshl_add_u64 v[2:3], s[12:13], 0, v[152:153]
	v_lshl_add_u64 v[0:1], s[12:13], 0, v[148:149]
	v_lshl_add_u64 v[6:7], s[24:25], 0, v[144:145]
	s_cselect_b64 s[12:13], -1, 0
	s_cmp_lg_u32 s5, 1
	v_lshl_add_u64 v[10:11], s[24:25], 0, v[146:147]
	s_cbranch_scc1 .LBB0_579
	s_barrier
	s_setprio 1

.LBB0_724:
	s_ashr_i32 s6, s14, 3
	s_lshl_b32 s7, s13, 22
	s_add_u32 s42, s34, s7
	s_addc_u32 s43, s35, 0
	s_add_u32 s44, s36, s7
	s_addc_u32 s45, s37, 0
	s_add_i32 s0, s0, s6
	s_ashr_i32 s6, s0, 31
	s_lshr_b32 s6, s6, 26
	s_add_i32 s6, s0, s6
	s_ashr_i32 s7, s6, 6
	s_and_b32 s6, s6, 0xffc0
	s_sub_i32 s6, s0, s6
	s_bfe_i32 s0, s6, 0x80000
	s_bfe_u32 s0, s0, 0x3000c
	s_add_i32 s16, s6, s0
	s_bfe_i32 s0, s16, 0x80000
	s_and_b32 s16, s16, 0xf8
	s_sub_i32 s6, s6, s16
	s_lshl_b32 s7, s7, 3
	s_sext_i32_i16 s0, s0
	s_sext_i32_i8 s6, s6
	s_lshr_b32 s0, s0, 3
	s_add_i32 s18, s7, s6
	s_ashr_i32 s14, s12, 6
	s_ashr_i32 s19, s18, 31
	s_bfe_i64 s[16:17], s[0:1], 0x100000
	s_ashr_i32 s15, s12, 8
	s_lshl_b32 s46, s14, 10
	s_lshl_b64 s[6:7], s[18:19], 19
	s_lshl_b64 s[16:17], s[16:17], 19
	s_add_u32 s24, s44, s16
	s_addc_u32 s25, s45, s17
	s_add_i32 s19, s46, 0
	s_add_i32 m0, s19, 0x10000
	v_lshl_add_u64 v[0:1], s[24:25], 0, v[130:131]
	global_load_lds_dwordx4 v[0:1], off
	s_add_i32 m0, s19, 0x12000
	s_add_u32 s16, s24, 0x40000
	v_lshl_add_u64 v[2:3], s[24:25], 0, v[134:135]
	s_addc_u32 s17, s25, 0
	global_load_lds_dwordx4 v[2:3], off
	s_add_i32 m0, s19, 0x14000
	v_lshl_add_u64 v[4:5], s[16:17], 0, v[130:131]
	global_load_lds_dwordx4 v[4:5], off
	s_add_i32 m0, s19, 0x16000
	s_add_u32 s28, s42, s6
	v_lshl_add_u64 v[4:5], s[16:17], 0, v[134:135]
	s_addc_u32 s29, s43, s7
	s_add_i32 s47, s19, 0x2000
	global_load_lds_dwordx4 v[4:5], off
	v_lshl_add_u64 v[6:7], s[28:29], 0, v[128:129]
	s_mov_b32 m0, s19
	s_add_u32 s6, s28, 0x40000
	global_load_lds_dwordx4 v[6:7], off
	v_lshl_add_u64 v[4:5], s[28:29], 0, v[132:133]
	s_mov_b32 m0, s47
	s_addc_u32 s7, s29, 0
	s_add_i32 s48, s19, 0x4000
	global_load_lds_dwordx4 v[4:5], off
	v_lshl_add_u64 v[8:9], s[6:7], 0, v[128:129]
	s_mov_b32 m0, s48
	s_add_i32 s49, s19, 0x6000
	global_load_lds_dwordx4 v[8:9], off
	v_lshl_add_u64 v[8:9], s[6:7], 0, v[132:133]
	s_mov_b32 m0, s49
	s_cmp_eq_u32 s15, 1
	global_load_lds_dwordx4 v[8:9], off
	s_cselect_b64 s[6:7], -1, 0
	s_cmp_lg_u32 s15, 1
	s_cbranch_scc1 .LBB0_726
	s_barrier
	s_setprio 1

.LBB0_760:
	s_setprio 0
	v_readlane_b32 s4, v252, 0
	s_add_i32 s4, s4, 1
	s_mov_b32 s0, s4
	v_readlane_b32 s5, v252, 1
	v_writelane_b32 v252, s0, 0
	v_readlane_b32 s38, v254, 55
	v_readlane_b32 s39, v254, 56
	v_writelane_b32 v252, s1, 1
	s_nop 0
	v_readlane_b32 s0, v252, 7
	s_cmp_ge_i32 s4, s0
	s_mov_b64 s[4:5], -1
	s_cbranch_scc1 .LBB0_11
	v_readlane_b32 s4, v252, 40
	v_readlane_b32 s5, v252, 41
	s_andn2_b64 vcc, exec, s[4:5]
	s_cbranch_vccnz .LBB0_773
	s_waitcnt vmcnt(0) lgkmcnt(0)
	s_barrier
	s_mov_b64 s[4:5], exec
	v_readlane_b32 s6, v254, 2
	v_readlane_b32 s7, v254, 3
	s_and_b64 s[6:7], s[4:5], s[6:7]
	s_mov_b64 exec, s[6:7]
	s_cbranch_execz .LBB0_772
	v_readlane_b32 s6, v252, 4
	v_readlane_b32 s7, v252, 5
	buffer_wbl2 sc1
	s_load_dwordx2 s[6:7], s[6:7], 0x58
	s_mov_b64 s[8:9], exec
	v_mbcnt_lo_u32_b32 v1, s8, 0
	v_mbcnt_hi_u32_b32 v1, s9, v1
	v_cmp_eq_u32_e32 vcc, 0, v1
	s_waitcnt lgkmcnt(0)
	global_load_dword v0, v153, s[6:7] offset:40
	s_and_saveexec_b64 s[10:11], vcc
	s_cbranch_execz .LBB0_765
	s_bcnt1_i32_b64 s0, s[8:9]
	v_mov_b32_e32 v2, s0
	global_atomic_add v2, v153, v2, s[6:7] offset:32 sc0
